# pass2 restructured: preparation of chunk ch+1 in the pre-barrier segment, waves 0-3 prepare->MFMA part and 4-7 the reverse, raw rows written behind barrier 1, out tile in own LDS region; on top of v11
# baseline (speedup 1.0000x reference)
.LBB0_1328:
	s_or_b64 exec, exec, s[22:23]
	s_lshl_b32 s19, s24, 1
	s_and_b32 s22, s25, 0xf00
	s_and_b32 s23, s19, 0x300
	s_lshl_b32 s19, s26, 2
	s_add_u32 s20, s22, s20
	v_or_b32_e32 v60, s27, v107
	s_addc_u32 s21, 0, s21
	v_mov_b32_e32 v58, s23
	v_mov_b32_e32 v59, v16
	v_lshlrev_b32_e32 v123, 1, v60
	v_lshl_add_u64 v[60:61], s[20:21], 0, v[74:75]
	s_movk_i32 s22, 0x1600
	s_waitcnt vmcnt(0)
	v_add_u32_e32 v196, 0xe400, v93
	v_add_u32_e32 v197, 0xe400, v94
	v_add_u32_e32 v196, v196, v80
	v_add_u32_e32 v197, v197, v80
	ds_write_b128 v196, v[8:11]
	ds_write_b128 v197, v[12:15] offset:17408
	ds_write_b128 v197, v[18:21] offset:37888
	ds_write_b128 v196, v[22:25] offset:48128
	s_waitcnt lgkmcnt(0)
	s_barrier
	v_lshlrev_b64 v[62:63], 11, v[60:61]
	v_mad_u64_u32 v[58:59], s[20:21], v60, s22, v[58:59]
	v_or_b32_e32 v62, s23, v62
	v_mad_i32_i24 v59, v61, s22, v59
	s_waitcnt vmcnt(12)
	v_lshlrev_b32_e32 v26, 16, v38
	v_and_b32_e32 v27, 0xffff0000, v38
	v_lshlrev_b32_e32 v28, 16, v39
	v_and_b32_e32 v29, 0xffff0000, v39
	s_waitcnt vmcnt(11)
	v_lshlrev_b32_e32 v30, 16, v34
	v_and_b32_e32 v31, 0xffff0000, v34
	v_lshlrev_b32_e32 v32, 16, v35
	v_and_b32_e32 v33, 0xffff0000, v35
	s_waitcnt vmcnt(10)
	v_lshlrev_b32_e32 v34, 16, v36
	v_and_b32_e32 v35, 0xffff0000, v36
	v_lshlrev_b32_e32 v36, 16, v37
	v_and_b32_e32 v37, 0xffff0000, v37
	s_waitcnt vmcnt(9)
	v_lshlrev_b32_e32 v38, 16, v40
	v_and_b32_e32 v39, 0xffff0000, v40
	v_lshlrev_b32_e32 v40, 16, v41
	v_and_b32_e32 v41, 0xffff0000, v41
	s_waitcnt vmcnt(8)
	v_lshlrev_b32_e32 v42, 16, v44
	v_and_b32_e32 v43, 0xffff0000, v44
	v_lshlrev_b32_e32 v44, 16, v45
	v_and_b32_e32 v45, 0xffff0000, v45
	s_waitcnt vmcnt(7)
	v_lshlrev_b32_e32 v46, 16, v48
	v_and_b32_e32 v47, 0xffff0000, v48
	v_lshlrev_b32_e32 v48, 16, v49
	v_and_b32_e32 v49, 0xffff0000, v49
	s_waitcnt vmcnt(6)
	v_lshlrev_b32_e32 v50, 16, v52
	v_and_b32_e32 v51, 0xffff0000, v52
	v_lshlrev_b32_e32 v52, 16, v53
	v_and_b32_e32 v53, 0xffff0000, v53
	s_waitcnt vmcnt(5)
	v_lshlrev_b32_e32 v54, 16, v56
	v_and_b32_e32 v55, 0xffff0000, v56
	v_lshlrev_b32_e32 v56, 16, v57
	v_and_b32_e32 v57, 0xffff0000, v57
	v_add_lshl_u32 v124, s27, v77, 2
	v_lshl_or_b32 v222, s27, 1, v104
	v_add_u32_e32 v237, 0x1c800, v109
	v_add_u32_e32 v238, 0x1c800, v93
	v_add_u32_e32 v237, v237, v222
	v_add_u32_e32 v238, v238, v80
	v_mul_u32_u24_e32 v236, 0x140, v95
	v_lshlrev_b32_e32 v224, 1, v222
	v_add_u32_e32 v236, v236, v222
	global_load_dwordx4 v[224:227], v224, s[70:71]
	v_lshl_add_u64 v[88:89], v[82:83], 0, v[62:63]
	v_lshl_add_u64 v[90:91], v[84:85], 0, v[58:59]
	global_load_dwordx4 v[180:183], v[90:91], off offset:-2048
	global_load_dwordx4 v[184:187], v[90:91], off offset:-1024
	global_load_dwordx4 v[188:191], v[90:91], off
	global_load_dwordx4 v[192:195], v[90:91], off offset:1024
	s_mov_b32 s26, 0
.Lp2s_top:
	s_and_b32 s22, s26, 1
	s_mul_i32 s27, s22, 0xe400
	s_xor_b32 s20, s22, 1
	s_mul_i32 s28, s20, 0xe400
	s_cmp_gt_u32 s26, 4
	s_cbranch_scc1 .Lp2s_noload
	s_mov_b64 vcc, 0x2c000
	v_lshl_add_u64 v[196:197], v[90:91], 0, vcc
	s_bitcmp1_b32 s26, 0
	s_cbranch_scc1 .Lp2s_loadB
	global_load_dwordx4 v[8:11], v[196:197], off offset:-2048
	global_load_dwordx4 v[12:15], v[196:197], off offset:-1024
	global_load_dwordx4 v[18:21], v[196:197], off
	global_load_dwordx4 v[22:25], v[196:197], off offset:1024
	s_branch .Lp2s_noload
.Lp2s_loadB:
	global_load_dwordx4 v[180:183], v[196:197], off offset:-2048
	global_load_dwordx4 v[184:187], v[196:197], off offset:-1024
	global_load_dwordx4 v[188:191], v[196:197], off
	global_load_dwordx4 v[192:195], v[196:197], off offset:1024
.Lp2s_noload:
	s_cmp_eq_u32 s26, 0
	s_cbranch_scc1 .Lp2s_noH
	ds_read_b128 v[58:61], v238
	s_waitcnt lgkmcnt(0)
	global_store_dwordx4 v[88:89], v[58:61], off
	s_mov_b64 vcc, 0x10000
	v_lshl_add_u64 v[88:89], v[88:89], 0, vcc
.Lp2s_noH:
	s_cmp_ge_u32 s19, 16
	s_cbranch_scc1 .Lp2s_CD
.Lp2s_E:
	s_cmp_eq_u32 s26, 7
	s_cbranch_scc1 .Lp2s_Edone
	v_add3_u32 v68, s28, v96, v120
	ds_read_b64_tr_b16 v[66:67], v68 offset:17408
	ds_read_b64_tr_b16 v[68:69], v68 offset:18688
	v_add_u32_e32 v138, s28, v236
	v_add3_u32 v139, s28, v109, v222
	ds_read_b64 v[148:149], v138 offset:17408
	ds_read_b64 v[150:151], v138 offset:22528
	ds_read_b64 v[152:153], v139
	ds_read_b64 v[154:155], v139 offset:4352
	s_waitcnt lgkmcnt(4)
	v_mfma_f32_16x16x32_bf16 v[70:73], v[66:69], v[4:7], 0
	v_mfma_f32_16x16x32_bf16 v[66:69], v[66:69], v[0:3], 0
	s_mov_b32 s23, 0x42e60000
	s_waitcnt lgkmcnt(0)
	v_lshlrev_b32_e32 v156, 16, v148
	v_and_b32_e32 v157, 0xffff0000, v148
	v_lshlrev_b32_e32 v158, 16, v149
	v_and_b32_e32 v159, 0xffff0000, v149
	v_lshlrev_b32_e32 v160, 16, v150
	v_and_b32_e32 v161, 0xffff0000, v150
	v_lshlrev_b32_e32 v162, 16, v151
	v_and_b32_e32 v163, 0xffff0000, v151
	v_lshlrev_b32_e32 v196, 16, v152
	v_and_b32_e32 v197, 0xffff0000, v152
	v_lshlrev_b32_e32 v198, 16, v153
	v_and_b32_e32 v199, 0xffff0000, v153
	v_lshlrev_b32_e32 v200, 16, v154
	v_and_b32_e32 v201, 0xffff0000, v154
	v_lshlrev_b32_e32 v202, 16, v155
	v_and_b32_e32 v203, 0xffff0000, v155
	v_exp_f32_e32 v156, v156
	v_exp_f32_e32 v157, v157
	v_exp_f32_e32 v158, v158
	v_exp_f32_e32 v159, v159
	v_exp_f32_e32 v160, v160
	v_exp_f32_e32 v161, v161
	v_exp_f32_e32 v162, v162
	v_exp_f32_e32 v163, v163
	v_sub_f32_e32 v156, 1.0, v156
	v_sub_f32_e32 v157, 1.0, v157
	v_sub_f32_e32 v158, 1.0, v158
	v_sub_f32_e32 v159, 1.0, v159
	v_sub_f32_e32 v160, 1.0, v160
	v_sub_f32_e32 v161, 1.0, v161
	v_sub_f32_e32 v162, 1.0, v162
	v_sub_f32_e32 v163, 1.0, v163
	v_exp_f32_e32 v204, v70
	v_exp_f32_e32 v205, v71
	v_exp_f32_e32 v206, v72
	v_exp_f32_e32 v207, v73
	v_exp_f32_e32 v208, v66
	v_exp_f32_e32 v209, v67
	v_exp_f32_e32 v210, v68
	v_exp_f32_e32 v211, v69
	v_sub_f32_dpp v126, v66, v70 row_newbcast:15 row_mask:0xf bank_mask:0xf
	v_sub_f32_dpp v127, v67, v71 row_newbcast:15 row_mask:0xf bank_mask:0xf
	v_sub_f32_dpp v128, v68, v72 row_newbcast:15 row_mask:0xf bank_mask:0xf
	v_sub_f32_dpp v129, v69, v73 row_newbcast:15 row_mask:0xf bank_mask:0xf
	v_sub_f32_dpp v130, v66, v66 row_newbcast:15 row_mask:0xf bank_mask:0xf
	v_sub_f32_dpp v131, v67, v67 row_newbcast:15 row_mask:0xf bank_mask:0xf
	v_sub_f32_dpp v132, v68, v68 row_newbcast:15 row_mask:0xf bank_mask:0xf
	v_sub_f32_dpp v133, v69, v69 row_newbcast:15 row_mask:0xf bank_mask:0xf
	v_mul_f32_e32 v196, v196, v204
	v_mul_f32_e32 v197, v197, v205
	v_mul_f32_e32 v198, v198, v206
	v_mul_f32_e32 v199, v199, v207
	v_mul_f32_e32 v200, v200, v208
	v_mul_f32_e32 v201, v201, v209
	v_mul_f32_e32 v202, v202, v210
	v_mul_f32_e32 v203, v203, v211
	v_min_f32_e64 v204, -v70, s23
	v_min_f32_e64 v205, -v71, s23
	v_min_f32_e64 v206, -v72, s23
	v_min_f32_e64 v207, -v73, s23
	v_min_f32_e64 v208, -v66, s23
	v_min_f32_e64 v209, -v67, s23
	v_min_f32_e64 v210, -v68, s23
	v_min_f32_e64 v211, -v69, s23
	v_exp_f32_e32 v126, v126
	v_exp_f32_e32 v127, v127
	v_exp_f32_e32 v128, v128
	v_exp_f32_e32 v129, v129
	v_exp_f32_e32 v130, v130
	v_exp_f32_e32 v131, v131
	v_exp_f32_e32 v132, v132
	v_exp_f32_e32 v133, v133
	v_exp_f32_e32 v204, v204
	v_exp_f32_e32 v205, v205
	v_exp_f32_e32 v206, v206
	v_exp_f32_e32 v207, v207
	v_exp_f32_e32 v208, v208
	v_exp_f32_e32 v209, v209
	v_exp_f32_e32 v210, v210
	v_exp_f32_e32 v211, v211
	v_exp_f32_e32 v212, v66
	v_exp_f32_e32 v213, v67
	v_exp_f32_e32 v214, v68
	v_exp_f32_e32 v215, v69
	v_mul_f32_e32 v126, v126, v156
	v_mul_f32_e32 v127, v127, v157
	v_mul_f32_e32 v128, v128, v158
	v_mul_f32_e32 v129, v129, v159
	v_mul_f32_e32 v130, v130, v160
	v_mul_f32_e32 v131, v131, v161
	v_mul_f32_e32 v132, v132, v162
	v_mul_f32_e32 v133, v133, v163
	v_mul_f32_e32 v204, v204, v156
	v_mul_f32_e32 v205, v205, v157
	v_mul_f32_e32 v206, v206, v158
	v_mul_f32_e32 v207, v207, v159
	v_mul_f32_e32 v208, v208, v160
	v_mul_f32_e32 v209, v209, v161
	v_mul_f32_e32 v210, v210, v162
	v_mul_f32_e32 v211, v211, v163
	v_lshl_add_u32 v216, v222, 1, s28
	v_cvt_pk_bf16_f32 v148, v196, v197
	v_cvt_pk_bf16_f32 v149, v198, v199
	v_cvt_pk_bf16_f32 v150, v200, v201
	v_cvt_pk_bf16_f32 v151, v202, v203
	v_cvt_pk_bf16_f32 v152, v204, v205
	v_cvt_pk_bf16_f32 v153, v206, v207
	v_cvt_pk_bf16_f32 v154, v208, v209
	v_cvt_pk_bf16_f32 v155, v210, v211
	v_cvt_pk_bf16_f32 v134, v126, v127
	v_cvt_pk_bf16_f32 v135, v128, v129
	v_cvt_pk_bf16_f32 v136, v130, v131
	v_cvt_pk_bf16_f32 v137, v132, v133
	ds_write_b64 v139, v[148:149]
	ds_write_b64 v139, v[150:151] offset:4352
	ds_write_b64 v139, v[152:153] offset:8704
	ds_write_b64 v139, v[154:155] offset:13056
	ds_write_b64 v138, v[134:135] offset:27648
	ds_write_b64 v138, v[136:137] offset:32768
	s_and_saveexec_b64 s[20:21], s[2:3]
	ds_write_b128 v216, v[212:215] offset:56832
	s_or_b64 exec, exec, s[20:21]

.Lp2s_CD:
	v_add3_u32 v147, s27, v104, v109
	s_add_i32 s29, s27, s19
	ds_read_b64 v[148:149], v147
	ds_read_b64 v[150:151], v147 offset:32
	ds_read_b64 v[152:153], v147 offset:4352
	ds_read_b64 v[154:155], v147 offset:4384
	ds_read_b64 v[196:197], v147 offset:8704
	ds_read_b64 v[198:199], v147 offset:8736
	ds_read_b64 v[200:201], v147 offset:13056
	ds_read_b64 v[202:203], v147 offset:13088
	v_cvt_pk_bf16_f32 v126, v26, v27
	v_cvt_pk_bf16_f32 v127, v28, v29
	v_cvt_pk_bf16_f32 v128, v30, v31
	v_cvt_pk_bf16_f32 v129, v32, v33
	ds_read_b64 v[156:157], v147 offset:64
	ds_read_b64 v[158:159], v147 offset:96
	ds_read_b64 v[160:161], v147 offset:4416
	ds_read_b64 v[162:163], v147 offset:4448
	ds_read_b64 v[204:205], v147 offset:8768
	ds_read_b64 v[206:207], v147 offset:8800
	s_waitcnt lgkmcnt(12)
	v_mfma_f32_16x16x32_bf16 v[62:65], v[126:129], v[148:151], 0
	ds_read_b64 v[208:209], v147 offset:13120
	ds_read_b64 v[210:211], v147 offset:13152
	v_cvt_pk_bf16_f32 v130, v34, v35
	v_cvt_pk_bf16_f32 v131, v36, v37
	v_cvt_pk_bf16_f32 v132, v38, v39
	v_cvt_pk_bf16_f32 v133, v40, v41
	s_waitcnt lgkmcnt(12)
	v_mfma_f32_16x16x32_bf16 v[58:61], v[126:129], v[152:155], 0
	s_waitcnt lgkmcnt(10)
	v_mfma_f32_16x16x32_bf16 v[164:167], v[196:199], v[148:151], 0
	v_mfma_f32_16x16x32_bf16 v[168:171], v[196:199], v[152:155], 0
	s_waitcnt lgkmcnt(8)
	v_mfma_f32_16x16x32_bf16 v[172:175], v[200:203], v[152:155], 0
	ds_read_b64 v[148:149], v147 offset:128
	ds_read_b64 v[150:151], v147 offset:160
	ds_read_b64 v[152:153], v147 offset:4480
	ds_read_b64 v[154:155], v147 offset:4512
	ds_read_b64 v[196:197], v147 offset:8832
	ds_read_b64 v[198:199], v147 offset:8864
	s_waitcnt lgkmcnt(12)
	v_mfma_f32_16x16x32_bf16 v[62:65], v[130:133], v[156:159], v[62:65]
	ds_read_b64 v[200:201], v147 offset:13184
	ds_read_b64 v[202:203], v147 offset:13216
	v_cvt_pk_bf16_f32 v134, v42, v43
	v_cvt_pk_bf16_f32 v135, v44, v45
	v_cvt_pk_bf16_f32 v136, v46, v47
	v_cvt_pk_bf16_f32 v137, v48, v49
	s_waitcnt lgkmcnt(12)
	v_mfma_f32_16x16x32_bf16 v[58:61], v[130:133], v[160:163], v[58:61]
	s_waitcnt lgkmcnt(10)
	v_mfma_f32_16x16x32_bf16 v[164:167], v[204:207], v[156:159], v[164:167]
	v_mfma_f32_16x16x32_bf16 v[168:171], v[204:207], v[160:163], v[168:171]
	s_waitcnt lgkmcnt(8)
	v_mfma_f32_16x16x32_bf16 v[172:175], v[208:211], v[160:163], v[172:175]
	ds_read_b64 v[156:157], v147 offset:192
	ds_read_b64 v[158:159], v147 offset:224
	ds_read_b64 v[160:161], v147 offset:4544
	ds_read_b64 v[162:163], v147 offset:4576
	ds_read_b64 v[204:205], v147 offset:8896
	ds_read_b64 v[206:207], v147 offset:8928
	s_waitcnt lgkmcnt(12)
	v_mfma_f32_16x16x32_bf16 v[62:65], v[134:137], v[148:151], v[62:65]
	ds_read_b64 v[208:209], v147 offset:13248
	ds_read_b64 v[210:211], v147 offset:13280
	v_cvt_pk_bf16_f32 v138, v50, v51
	v_cvt_pk_bf16_f32 v139, v52, v53
	v_cvt_pk_bf16_f32 v140, v54, v55
	v_cvt_pk_bf16_f32 v141, v56, v57
	s_waitcnt lgkmcnt(12)
	v_mfma_f32_16x16x32_bf16 v[58:61], v[134:137], v[152:155], v[58:61]
	s_waitcnt lgkmcnt(10)
	v_mfma_f32_16x16x32_bf16 v[164:167], v[196:199], v[148:151], v[164:167]
	v_mfma_f32_16x16x32_bf16 v[168:171], v[196:199], v[152:155], v[168:171]
	s_waitcnt lgkmcnt(8)
	v_mfma_f32_16x16x32_bf16 v[172:175], v[200:203], v[152:155], v[172:175]
	v_add_u32_e32 v176, s27, v106
	v_add_u32_e32 v68, v176, v123
	ds_read_b64_tr_b16 v[66:67], v68 offset:37888
	ds_read_b64_tr_b16 v[68:69], v68 offset:43008
	s_waitcnt lgkmcnt(8)
	v_mfma_f32_16x16x32_bf16 v[62:65], v[138:141], v[156:159], v[62:65]
	s_waitcnt lgkmcnt(6)
	v_mfma_f32_16x16x32_bf16 v[58:61], v[138:141], v[160:163], v[58:61]
	s_waitcnt lgkmcnt(4)
	v_mfma_f32_16x16x32_bf16 v[164:167], v[204:207], v[156:159], v[164:167]
	v_mfma_f32_16x16x32_bf16 v[168:171], v[204:207], v[160:163], v[168:171]
	s_waitcnt lgkmcnt(2)
	v_mfma_f32_16x16x32_bf16 v[172:175], v[208:211], v[160:163], v[172:175]
	v_add_u32_e32 v125, s27, v105
	v_add_u32_e32 v134, v176, v110
	v_mov_b32_e32 v177, s55
	v_mov_b32_e32 v72, v16
	v_mov_b32_e32 v73, v16
	s_nop 0
	v_cndmask_b32_e64 v165, 0, v165, s[6:7]
	v_cndmask_b32_e64 v166, v166, 0, s[8:9]
	v_cndmask_b32_e64 v167, v167, 0, s[10:11]
	v_cndmask_b32_e64 v164, v164, v177, s[4:5]
	v_cvt_pk_bf16_f32 v70, v164, v165
	v_cvt_pk_bf16_f32 v71, v166, v167
	v_cndmask_b32_e64 v172, v172, v177, s[4:5]
	v_cndmask_b32_e64 v173, v173, 0, s[12:13]
	v_cndmask_b32_e64 v174, v174, 0, s[14:15]
	v_cndmask_b32_e64 v175, v175, 0, s[16:17]
	s_waitcnt lgkmcnt(0)
	v_mfma_f32_16x16x32_bf16 v[62:65], v[66:69], v[70:73], v[62:65]
	v_cvt_pk_bf16_f32 v70, v168, v169
	v_cvt_pk_bf16_f32 v71, v170, v171
	v_cvt_pk_bf16_f32 v72, v172, v173
	v_cvt_pk_bf16_f32 v73, v174, v175
	s_nop 1
	v_mfma_f32_16x16x32_bf16 v[58:61], v[66:69], v[70:73], v[58:61]
	ds_read_b128 v[70:73], v125 offset:56832
	ds_read_b64_tr_b16 v[128:129], v134 offset:32768
	ds_read_b64_tr_b16 v[126:127], v134 offset:27648
	ds_read_b64_tr_b16 v[130:131], v134 offset:27680
	s_waitcnt lgkmcnt(3)
	v_pk_mul_f32 v[26:27], v[26:27], v[70:71]
	v_add_u32_e32 v70, s27, v111
	v_pk_mul_f32 v[28:29], v[28:29], v[72:73]
	ds_read_b128 v[70:73], v70 offset:56832
	ds_read_b64_tr_b16 v[132:133], v134 offset:32800
	s_waitcnt lgkmcnt(3)
	v_mfma_f32_16x16x32_bf16 v[26:29], v[126:129], v[66:69], v[26:29]
	s_waitcnt lgkmcnt(1)
	v_pk_mul_f32 v[32:33], v[32:33], v[72:73]
	v_pk_mul_f32 v[30:31], v[30:31], v[70:71]
	ds_read_b128 v[70:73], v125 offset:56960
	ds_read_b64_tr_b16 v[126:127], v134 offset:27712
	ds_read_b64_tr_b16 v[128:129], v134 offset:32832
	s_waitcnt lgkmcnt(3)
	v_mfma_f32_16x16x32_bf16 v[30:33], v[130:133], v[66:69], v[30:33]
	s_waitcnt lgkmcnt(2)
	v_pk_mul_f32 v[36:37], v[36:37], v[72:73]
	v_pk_mul_f32 v[34:35], v[34:35], v[70:71]
	s_waitcnt lgkmcnt(0)
	s_nop 0
	v_mfma_f32_16x16x32_bf16 v[34:37], v[126:129], v[66:69], v[34:37]
	ds_read_b128 v[70:73], v125 offset:57024
	ds_read_b64_tr_b16 v[126:127], v134 offset:27744
	ds_read_b64_tr_b16 v[128:129], v134 offset:32864
	s_waitcnt lgkmcnt(2)
	v_pk_mul_f32 v[40:41], v[40:41], v[72:73]
	v_pk_mul_f32 v[38:39], v[38:39], v[70:71]
	s_waitcnt lgkmcnt(0)
	s_nop 0
	v_mfma_f32_16x16x32_bf16 v[38:41], v[126:129], v[66:69], v[38:41]
	ds_read_b128 v[70:73], v125 offset:57088
	ds_read_b64_tr_b16 v[126:127], v134 offset:27776
	ds_read_b64_tr_b16 v[128:129], v134 offset:32896
	s_waitcnt lgkmcnt(2)
	v_pk_mul_f32 v[44:45], v[44:45], v[72:73]
	v_pk_mul_f32 v[42:43], v[42:43], v[70:71]
	s_waitcnt lgkmcnt(0)
	s_nop 0
	v_mfma_f32_16x16x32_bf16 v[42:45], v[126:129], v[66:69], v[42:45]
	ds_read_b128 v[70:73], v125 offset:57152
	ds_read_b64_tr_b16 v[126:127], v134 offset:27808
	ds_read_b64_tr_b16 v[128:129], v134 offset:32928
	s_waitcnt lgkmcnt(2)
	v_pk_mul_f32 v[48:49], v[48:49], v[72:73]
	v_pk_mul_f32 v[46:47], v[46:47], v[70:71]
	s_waitcnt lgkmcnt(0)
	s_nop 0
	v_mfma_f32_16x16x32_bf16 v[46:49], v[126:129], v[66:69], v[46:49]
	ds_read_b128 v[70:73], v125 offset:57216
	ds_read_b64_tr_b16 v[126:127], v134 offset:27840
	ds_read_b64_tr_b16 v[128:129], v134 offset:32960
	s_waitcnt lgkmcnt(2)
	v_pk_mul_f32 v[52:53], v[52:53], v[72:73]
	v_pk_mul_f32 v[50:51], v[50:51], v[70:71]
	s_waitcnt lgkmcnt(0)
	s_nop 0
	v_mfma_f32_16x16x32_bf16 v[50:53], v[126:129], v[66:69], v[50:53]
	ds_read_b128 v[70:73], v125 offset:57280
	ds_read_b64_tr_b16 v[126:127], v134 offset:27872
	ds_read_b64_tr_b16 v[128:129], v134 offset:32992
	s_waitcnt lgkmcnt(2)
	v_pk_mul_f32 v[56:57], v[56:57], v[72:73]
	v_pk_mul_f32 v[54:55], v[54:55], v[70:71]
	s_waitcnt lgkmcnt(0)
	s_nop 0
	v_mfma_f32_16x16x32_bf16 v[54:57], v[126:129], v[66:69], v[54:57]
	v_mul_f32_e32 v148, v62, v62
	v_mul_f32_e32 v149, v58, v58
	v_fmac_f32_e32 v148, v63, v63
	v_fmac_f32_e32 v149, v59, v59
	v_fmac_f32_e32 v148, v64, v64
	v_fmac_f32_e32 v149, v60, v60
	v_fmac_f32_e32 v148, v65, v65
	v_fmac_f32_e32 v149, v61, v61
	v_lshl_add_u32 v156, v77, 5, s29
	s_nop 0
	v_permlane16_swap_b32_e32 v148, v149
	v_add_f32_e32 v148, v148, v149
	v_mov_b32_e32 v149, v148
	s_nop 1
	v_permlane32_swap_b32_e32 v148, v149
	v_add_f32_e32 v148, v148, v149
	s_mov_b64 s[22:23], exec
	s_mov_b32 exec_hi, 0
	ds_write_b32 v156, v148 offset:57344
	s_mov_b64 exec, s[22:23]
	v_add3_u32 v125, s27, v109, v222
	ds_read_b64 v[244:245], v125 offset:48128
	ds_read_b64 v[246:247], v125 offset:52480
	s_cmp_ge_u32 s19, 16
	s_cbranch_scc1 .Lp2s_E
.Lp2s_bar1:
	s_waitcnt lgkmcnt(0)
	s_barrier
	v_lshl_add_u32 v160, v95, 5, s27
	ds_read_b128 v[148:151], v160 offset:57344
	ds_read_b128 v[152:155], v160 offset:57360
	ds_read_b128 v[156:159], v160 offset:57856
	ds_read_b128 v[162:165], v160 offset:57872
	s_waitcnt vmcnt(8)
	s_waitcnt lgkmcnt(2)
	v_add_f32_e32 v170, v148, v149
	v_add_f32_e32 v171, v150, v151
	v_add_f32_e32 v172, v152, v153
	v_add_f32_e32 v170, v170, v171
	v_add_f32_e32 v173, v154, v155
	v_add_f32_e32 v172, v172, v173
	v_add_f32_e32 v170, v170, v172
	v_fmamk_f32 v170, v170, 0x3c000000, v218
	v_rsq_f32_e32 v170, v170
	s_waitcnt lgkmcnt(0)
	v_add_f32_e32 v174, v156, v157
	v_add_f32_e32 v175, v158, v159
	v_add_f32_e32 v176, v162, v163
	v_add_f32_e32 v174, v174, v175
	v_add_f32_e32 v177, v164, v165
	v_add_f32_e32 v176, v176, v177
	v_add_f32_e32 v174, v174, v176
	v_fmamk_f32 v174, v174, 0x3c000000, v218
	v_rsq_f32_e32 v174, v174
	s_waitcnt lgkmcnt(0)
	v_lshlrev_b32_e32 v178, 16, v244
	v_and_b32_e32 v179, 0xffff0000, v244
	v_lshlrev_b32_e32 v200, 16, v245
	v_and_b32_e32 v201, 0xffff0000, v245
	v_lshlrev_b32_e32 v202, 16, v246
	v_and_b32_e32 v203, 0xffff0000, v246
	v_lshlrev_b32_e32 v204, 16, v247
	v_and_b32_e32 v205, 0xffff0000, v247
	v_mul_f32_e32 v206, v62, v170
	v_mul_f32_e32 v207, v63, v170
	v_mul_f32_e32 v208, v64, v170
	v_mul_f32_e32 v209, v65, v170
	v_mul_f32_e32 v210, v58, v174
	v_mul_f32_e32 v211, v59, v174
	v_mul_f32_e32 v212, v60, v174
	v_mul_f32_e32 v213, v61, v174
	v_mul_f32_e32 v206, v224, v206
	v_mul_f32_e32 v207, v225, v207
	v_mul_f32_e32 v208, v226, v208
	v_mul_f32_e32 v209, v227, v209
	v_mul_f32_e32 v210, v224, v210
	v_mul_f32_e32 v211, v225, v211
	v_mul_f32_e32 v212, v226, v212
	v_mul_f32_e32 v213, v227, v213
	v_mul_f32_e32 v206, v206, v178
	v_mul_f32_e32 v207, v207, v179
	v_mul_f32_e32 v208, v208, v200
	v_mul_f32_e32 v209, v209, v201
	v_mul_f32_e32 v210, v210, v202
	v_mul_f32_e32 v211, v211, v203
	v_mul_f32_e32 v212, v212, v204
	v_mul_f32_e32 v213, v213, v205
	v_cvt_pk_bf16_f32 v148, v206, v207
	v_cvt_pk_bf16_f32 v149, v208, v209
	v_cvt_pk_bf16_f32 v150, v210, v211
	v_cvt_pk_bf16_f32 v151, v212, v213
	ds_write_b64 v237, v[148:149]
	ds_write_b64 v237, v[150:151] offset:4352
	s_cmp_gt_u32 s26, 5
	s_cbranch_scc1 .Lp2s_bar2
	v_add3_u32 v196, s27, v93, v80
	v_add3_u32 v197, s27, v94, v80
	s_bitcmp1_b32 s26, 0
	s_cbranch_scc1 .Lp2s_wA
	s_cmp_gt_u32 s26, 1
	s_cbranch_scc1 .Lp2s_wBmid
	s_waitcnt vmcnt(7)
	ds_write_b128 v196, v[180:183]
	s_waitcnt vmcnt(6)
	ds_write_b128 v197, v[184:187] offset:17408
	s_waitcnt vmcnt(5)
	ds_write_b128 v197, v[188:191] offset:37888
	s_waitcnt vmcnt(4)
	ds_write_b128 v196, v[192:195] offset:48128
	s_branch .Lp2s_bar2
.Lp2s_wBmid:
	s_waitcnt vmcnt(9)
	ds_write_b128 v196, v[180:183]
	s_waitcnt vmcnt(8)
	ds_write_b128 v197, v[184:187] offset:17408
	s_waitcnt vmcnt(7)
	ds_write_b128 v197, v[188:191] offset:37888
	s_waitcnt vmcnt(6)
	ds_write_b128 v196, v[192:195] offset:48128
	s_branch .Lp2s_bar2
.Lp2s_wA:
	s_cmp_eq_u32 s26, 5
	s_cbranch_scc1 .Lp2s_wAlast
	s_cmp_gt_u32 s26, 1
	s_cbranch_scc1 .Lp2s_wAmid
	s_waitcnt vmcnt(7)
	ds_write_b128 v196, v[8:11]
	s_waitcnt vmcnt(6)
	ds_write_b128 v197, v[12:15] offset:17408
	s_waitcnt vmcnt(5)
	ds_write_b128 v197, v[18:21] offset:37888
	s_waitcnt vmcnt(4)
	ds_write_b128 v196, v[22:25] offset:48128
	s_branch .Lp2s_bar2
.Lp2s_wAmid:
	s_waitcnt vmcnt(9)
	ds_write_b128 v196, v[8:11]
	s_waitcnt vmcnt(8)
	ds_write_b128 v197, v[12:15] offset:17408
	s_waitcnt vmcnt(7)
	ds_write_b128 v197, v[18:21] offset:37888
	s_waitcnt vmcnt(6)
	ds_write_b128 v196, v[22:25] offset:48128
	s_branch .Lp2s_bar2
.Lp2s_wAlast:
	s_waitcnt vmcnt(5)
	ds_write_b128 v196, v[8:11]
	s_waitcnt vmcnt(4)
	ds_write_b128 v197, v[12:15] offset:17408
	s_waitcnt vmcnt(3)
	ds_write_b128 v197, v[18:21] offset:37888
	s_waitcnt vmcnt(2)
	ds_write_b128 v196, v[22:25] offset:48128
.Lp2s_bar2:
	s_waitcnt lgkmcnt(0)
	s_barrier
	s_mov_b64 vcc, 0x2c000
	v_lshl_add_u64 v[90:91], v[90:91], 0, vcc
	s_add_i32 s26, s26, 1
	s_cmp_lt_u32 s26, 8
	s_cbranch_scc1 .Lp2s_top
	ds_read_b128 v[58:61], v238
	s_waitcnt lgkmcnt(0)
	global_store_dwordx4 v[88:89], v[58:61], off
	s_branch .LBB0_1325
